# grid barrier: last cross-XCD arriver bumps all per-XCD release words directly, leaders spin on own word (one poll hop less)
# speedup vs baseline: 1.0136x; 1.0136x over previous
.LBB0_598:
	s_or_b64 exec, exec, s[2:3]
	v_cvt_f32_u32_e32 v4, v2
	s_waitcnt vmcnt(0)
	v_readfirstlane_b32 s2, v3
	v_sub_u32_e32 v3, 0, v2
	v_rcp_iflag_f32_e32 v4, v4
	v_add_u32_e32 v5, s2, v1
	v_mul_f32_e32 v4, 0x4f7ffffe, v4
	v_cvt_u32_f32_e32 v4, v4
	v_mul_lo_u32 v1, v3, v4
	v_mul_hi_u32 v1, v4, v1
	v_add_u32_e32 v1, v4, v1
	v_mul_hi_u32 v1, v5, v1
	v_mul_lo_u32 v3, v1, v2
	v_sub_u32_e32 v3, v5, v3
	v_add_u32_e32 v4, 1, v1
	v_cmp_ge_u32_e32 vcc, v3, v2
	s_nop 1
	v_cndmask_b32_e32 v1, v1, v4, vcc
	v_sub_u32_e32 v4, v3, v2
	v_cndmask_b32_e32 v3, v3, v4, vcc
	v_add_u32_e32 v4, 1, v1
	v_cmp_ge_u32_e32 vcc, v3, v2
	v_add_u32_e32 v3, 1, v5
	s_nop 0
	v_cndmask_b32_e32 v1, v1, v4, vcc
	v_mul_lo_u32 v4, v2, v1
	v_add_u32_e32 v2, v4, v2
	v_cmp_ne_u32_e32 vcc, v3, v2
	s_cbranch_vccnz .Lxb_spin
	v_mov_b32_e32 v6, v1
	buffer_wbl2 sc1
	s_waitcnt vmcnt(0) lgkmcnt(0)
	v_readlane_b32 s2, v253, 15
	v_readlane_b32 s3, v253, 16
	v_mov_b32_e32 v2, 1
	s_nop 4
	global_atomic_add v2, v9, v2, s[2:3] sc0
	s_waitcnt vmcnt(0)
	v_mov_b32_e32 v1, v2
	v_cvt_f32_u32_e32 v2, v0
	v_sub_u32_e32 v3, 0, v0
	v_rcp_iflag_f32_e32 v2, v2
	s_nop 1
	v_mul_f32_e32 v2, 0x4f7ffffe, v2
	v_cvt_u32_f32_e32 v2, v2
	v_mul_lo_u32 v3, v3, v2
	v_mul_hi_u32 v3, v2, v3
	v_add_u32_e32 v2, v2, v3
	v_mul_hi_u32 v2, v1, v2
	v_mul_lo_u32 v3, v2, v0
	v_sub_u32_e32 v3, v1, v3
	v_cmp_ge_u32_e32 vcc, v3, v0
	v_add_u32_e32 v4, 1, v2
	v_add_u32_e32 v1, 1, v1
	v_cndmask_b32_e32 v2, v2, v4, vcc
	v_sub_u32_e32 v4, v3, v0
	v_cndmask_b32_e32 v3, v3, v4, vcc
	v_cmp_ge_u32_e32 vcc, v3, v0
	v_add_u32_e32 v3, 1, v2
	s_nop 0
	v_cndmask_b32_e32 v2, v2, v3, vcc
	v_mul_lo_u32 v3, v0, v2
	v_add_u32_e32 v0, v3, v0
	v_cmp_ne_u32_e32 vcc, v1, v0
	v_mov_b32_e32 v1, v6
	v_mov_b32_e32 v2, 1
	s_cbranch_vccnz .Lxb_spin
	global_atomic_add v9, v2, s[2:3] offset:-4096
	global_atomic_add v9, v2, s[2:3] offset:-3840
	global_atomic_add v9, v2, s[2:3] offset:-3584
	global_atomic_add v9, v2, s[2:3] offset:-3328
	global_atomic_add v9, v2, s[2:3] offset:-3072
	global_atomic_add v9, v2, s[2:3] offset:-2816
	global_atomic_add v9, v2, s[2:3] offset:-2560
	global_atomic_add v9, v2, s[2:3] offset:-2304
	global_atomic_add v9, v2, s[2:3] offset:-2048
	global_atomic_add v9, v2, s[2:3] offset:-1792
	global_atomic_add v9, v2, s[2:3] offset:-1536
	global_atomic_add v9, v2, s[2:3] offset:-1280
	global_atomic_add v9, v2, s[2:3] offset:-1024
	global_atomic_add v9, v2, s[2:3] offset:-768
	global_atomic_add v9, v2, s[2:3] offset:-512
	global_atomic_add v9, v2, s[2:3] offset:-256
	s_mov_b64 s[2:3], 0
	s_branch .Lxb_acq
.Lxb_spin:
	s_mov_b64 vcc, exec
	s_and_saveexec_b64 s[2:3], vcc
	s_xor_b64 s[2:3], exec, s[2:3]
	s_cbranch_execz .LBB0_612
	v_readlane_b32 s4, v253, 13
	v_readlane_b32 s5, v253, 14
	s_waitcnt lgkmcnt(0)
	s_nop 3
	global_load_dword v0, v9, s[4:5] sc1
	s_waitcnt vmcnt(0)
	v_cmp_eq_u32_e32 vcc, v0, v1
	s_and_saveexec_b64 s[4:5], vcc
	s_cbranch_execz .LBB0_611
	s_mov_b32 s28, 1
	s_mov_b64 s[6:7], 0
	s_branch .LBB0_602

.Lxb_acq:
	s_waitcnt vmcnt(0)
	buffer_inv sc1
	s_waitcnt vmcnt(0)
.LBB0_612:
	s_andn2_saveexec_b64 s[2:3], s[2:3]
	s_cbranch_execz .LBB0_632
.LBB0_632:
	s_or_b64 exec, exec, s[0:1]
	s_mov_b64 s[0:1], 0
	s_waitcnt lgkmcnt(0)
	s_barrier
